# P1 GEMM K-loop restructured: 64 MFMAs per barrier pair, all fragments loaded in the load segment (spare VGPRs), half-specific tile staging
# baseline (speedup 1.0000x reference)
; #define PG8_STAGE(bufoff, gbase, voff) do { _Pragma("unroll") for (int _i = 0; _i < 2; ++_i) \
;         __builtin_amdgcn_global_load_lds((const unsigned*)((const char*)(gbase) + (voff)[_i]), (PG8_LAS unsigned*)(lds + (bufoff) + ldsw + _i * 8192), 16, 0, 0); } while (0)
; #define PG8_WAIT_V(n) asm volatile("s_waitcnt vmcnt(" #n ")" ::: "memory")
; #define PG8_BAR __builtin_amdgcn_s_barrier()
; template <class Epi, class Sched, bool ALIGN_EPI = false, bool SP2 = false>
; __device__ __forceinline__ void gemm_phase(PG8_LAS unsigned char* lds, const Gemm g, const Sched& S, const Epi& E) {
;     ...
;     const int tid = tid_o, wid = __builtin_amdgcn_readfirstlane(tid >> 6), lane = tid & 63, wr = wid >> 2, wc = wid & 3, fr = lane & 15, fq = lane >> 4;
;     const int K = g.K, nt = K / BK;
;     unsigned voffA[2], voffB[2];
; #pragma unroll
;     for (int i = 0; i < 2; ++i) { int R, C; stage_rc(tid * 16 + i * 8192, R, C); const int Rb = Epi::PERM ? ((R & ~31) + perm32(R & 31)) : R;
;         voffA[i] = (unsigned)(R * K + C) * 2u; voffB[i] = (unsigned)(Rb * K + C) * 2u; }
;     const size_t kstep = (size_t)(BK * 2);
;     const size_t hstep = (size_t)HALF * K * 2;
;     const size_t tstep = 2 * hstep;
;     const unsigned ldsw = (unsigned)wid * 1024u;
;     const int aoff = lds_byte(wr * 64 + fr, fq * 8), boff = lds_byte(wc * 32 + fr, fq * 8);
;     ...
;     if constexpr (SP2) {
;         PG8_STAGE(PG8_SB(0, 0), cB, voffB); PG8_STAGE(PG8_SB(0, 1), cB + hstep, voffB); PG8_STAGE(PG8_SA(0, 0), cA, voffA); PG8_STAGE(PG8_SA(0, 1), cA + hstep, voffA);
;         if (wr == 1) PG8_BAR;
;         PG8_WAIT_V(2); PG8_BAR;
;         PG8_STAGE(PG8_SB(1, 0), cB + kstep, voffB); PG8_STAGE(PG8_SA(1, 0), cA + kstep, voffA); PG8_STAGE(PG8_SB(1, 1), cB + hstep + kstep, voffB);
;         PG8_WAIT_V(6); PG8_BAR;
.LBB0_121:
	s_lshl_b32 s8, s8, 5
	s_and_b32 s66, s8, 0x60
	s_mov_b64 s[8:9], 0x80
	s_add_i32 m0, s15, 0x18000
	v_lshl_add_u64 v[6:7], v[6:7], 0, s[8:9]
	s_lshl_b32 s11, s10, 13
	s_lshl_b32 s67, s66, 7
	s_waitcnt vmcnt(0)
	s_barrier
	global_load_lds_dwordx4 v[6:7], off
	v_lshl_add_u64 v[4:5], v[4:5], 0, s[8:9]
	s_add_i32 m0, s15, 0x1a000
	s_add_i32 s69, s15, 0x8000
	s_add_i32 s80, s15, 0xa000
	global_load_lds_dwordx4 v[4:5], off
	v_lshl_add_u64 v[0:1], v[0:1], 0, s[8:9]
	s_mov_b32 m0, s69
	s_add_u32 s12, s92, 0x80080
	global_load_lds_dwordx4 v[0:1], off
	v_lshl_add_u64 v[0:1], v[2:3], 0, s[8:9]
	s_mov_b32 m0, s80
	s_addc_u32 s13, s93, 0
	global_load_lds_dwordx4 v[0:1], off
	s_add_i32 m0, s15, 0x1c000
	v_lshl_add_u64 v[0:1], s[12:13], 0, v[132:133]
	global_load_lds_dwordx4 v[0:1], off
	v_lshl_add_u64 v[0:1], s[12:13], 0, v[128:129]
	s_add_i32 m0, s15, 0x1e000
	s_cmpk_lt_u32 s5, 0x100
	global_load_lds_dwordx4 v[0:1], off
	v_lshrrev_b32_e32 v1, 1, v9
	v_and_b32_e32 v2, 24, v1
	v_and_b32_e32 v0, 15, v9
	v_lshlrev_b32_e32 v1, 1, v2
	v_lshl_or_b32 v155, s10, 6, v0
	v_lshl_or_b32 v0, v0, 6, v1
	v_lshlrev_b32_e32 v1, 2, v9
	v_and_b32_e32 v1, 32, v1
	v_bitop3_b32 v3, v0, s11, v1 bitop3:0xde
	v_bitop3_b32 v159, v0, s67, v1 bitop3:0xde
	v_lshlrev_b32_e32 v0, 2, v2
	v_mov_b32_e32 v1, v133
	v_lshl_add_u64 v[136:137], s[58:59], 0, v[0:1]
	v_lshlrev_b32_e32 v0, 15, v13
	v_and_b32_e32 v0, 0xffff0000, v0
	v_lshl_add_u32 v0, v12, 12, v0
	v_and_b32_e32 v1, 1, v13
	v_lshl_or_b32 v0, v1, 6, v0
	v_lshl_add_u32 v138, v14, 1, v0
	v_lshlrev_b32_e32 v0, 15, v8
	v_and_b32_e32 v0, 0xffff0000, v0
	s_waitcnt vmcnt(6)
	v_lshl_add_u32 v0, v10, 12, v0
	v_and_b32_e32 v1, 1, v8
	s_cselect_b64 s[10:11], -1, 0
	v_lshl_or_b32 v0, v1, 6, v0
	s_add_i32 s81, 0, 0x10000
	s_add_i32 s89, 0, 0x14000
	s_sext_i32_i16 s97, s4
	v_or_b32_e32 v163, s66, v2
	v_mov_b32_e32 v139, v133
	v_lshl_add_u32 v140, v11, 1, v0
	v_mov_b32_e32 v141, v133
	v_mov_b64_e32 v[142:143], 0x580
	v_mov_b64_e32 v[144:145], 0x57f
	v_add_u32_e32 v167, s81, v159
	v_add_u32_e32 v173, s89, v159
	v_add_u32_e32 v175, 0, v3
	v_mbcnt_hi_u32_b32 v176, -1, v216
	v_mov_b32_e32 v177, 0x358637bd
	s_movk_i32 s96, 0x2c00
	s_barrier
	s_branch .LBB0_124

; #define PG8_STAGE(bufoff, gbase, voff) do { _Pragma("unroll") for (int _i = 0; _i < 2; ++_i) \
;         __builtin_amdgcn_global_load_lds((const unsigned*)((const char*)(gbase) + (voff)[_i]), (PG8_LAS unsigned*)(lds + (bufoff) + ldsw + _i * 8192), 16, 0, 0); } while (0)
; #define PG8_LDA(dst, b, h) do { _Pragma("unroll") for (int m = 0; m < 4; ++m) _Pragma("unroll") for (int k = 0; k < 2; ++k) dst[m][k] = *(const PG8_LAS bf16x8*)(lds + PG8_SA(b, h) + aoff + m * 2048 + k * 1024); } while (0)
; #define PG8_LDB(dst, b, h) do { _Pragma("unroll") for (int n = 0; n < 2; ++n) _Pragma("unroll") for (int k = 0; k < 2; ++k) dst[n][k] = *(const PG8_LAS bf16x8*)(lds + PG8_SB(b, h) + boff + n * 2048 + k * 1024); } while (0)
; #define PG8_WAIT_V(n) asm volatile("s_waitcnt vmcnt(" #n ")" ::: "memory")
; template <class Epi, class Sched, bool ALIGN_EPI = false, bool SP2 = false>
; __device__ __forceinline__ void gemm_phase(PG8_LAS unsigned char* lds, const Gemm g, const Sched& S, const Epi& E) {
;     ...
;     f32x4 acc[2][2][4][2];
; #pragma unroll
;     for (int a = 0; a < 2; ++a)
; #pragma unroll
;         for (int b = 0; b < 2; ++b)
; #pragma unroll
;             for (int m = 0; m < 4; ++m)
; #pragma unroll
;                 for (int n = 0; n < 2; ++n) acc[a][b][m][n] = (f32x4){0.f, 0.f, 0.f, 0.f};
;     ...
;         const bool has_next = S.next(ui + 1, nxt);
;         const char* nA = has_next ? (const char*)g.A + (size_t)nxt.pm * tstep : cA; const char* nB = has_next ? (const char*)g.Bt + (size_t)nxt.pn * tstep : cB;
;         for (int t = 0; t < nt; t += 2) {
;             const bool last = (t == nt - 2);
;             const char* a1 = cA + (size_t)(t + 1) * kstep;
;             const char* a2 = last ? nA : cA + (size_t)(t + 2) * kstep; const char* b2 = last ? nB : cB + (size_t)(t + 2) * kstep;
;             const char* a3 = a2 + kstep; const char* b3 = b2 + kstep;
;             if (last && has_next) S.a_ready(nxt);
;             if constexpr (SP2) {
;             PG8_LDB(B0, 0, 0); PG8_LDB(B1, 0, 1); PG8_SCHED; PG8_LDA(At, 0, 0); PG8_STAGE(PG8_SA(1, 1), a1 + hstep, voffA);
;             PG8_WAIT_V(8); PG8_WAIT_L(0); PG8_BAR; PG8_MMA(0, 0, At, B0); PG8_MMA(0, 1, At, B1); PG8_BAR; PG8_SCHED;
;             PG8_LDA(At, 0, 1); PG8_STAGE(PG8_SB(0, 0), b2, voffB); PG8_STAGE(PG8_SB(0, 1), b2 + hstep, voffB); PG8_STAGE(PG8_SA(0, 0), a2, voffA);
.LBB0_126:
	s_ashr_i32 s73, s72, 31
	s_lshl_b64 s[12:13], s[72:73], 20
	s_add_u32 s82, s40, s12
	s_addc_u32 s83, s41, s13
	s_and_b64 s[12:13], s[4:5], exec
	s_cselect_b32 s12, s83, s91
	s_cselect_b32 s13, s82, s90
	s_ashr_i32 s71, s70, 31
	s_lshl_b64 s[66:67], s[70:71], 20
	s_add_u32 s86, s78, s66
	s_addc_u32 s87, s79, s67
	s_and_b64 s[66:67], s[4:5], exec
	s_cselect_b32 s71, s87, s93
	s_cselect_b32 s73, s86, s92
	s_add_u32 s90, s90, 0x80080
	s_addc_u32 s91, s91, 0
	s_add_u32 vcc_lo, s92, 0x100
	v_mov_b64_e32 v[0:1], 0
	v_mov_b64_e32 v[2:3], 0
	v_mov_b64_e32 v[4:5], 0
	v_mov_b64_e32 v[6:7], 0
	v_mov_b64_e32 v[8:9], 0
	v_mov_b64_e32 v[10:11], 0
	v_mov_b64_e32 v[12:13], 0
	v_mov_b64_e32 v[14:15], 0
	v_mov_b64_e32 v[16:17], 0
	v_mov_b64_e32 v[18:19], 0
	v_mov_b64_e32 v[20:21], 0
	v_mov_b64_e32 v[22:23], 0
	v_mov_b64_e32 v[24:25], 0
	v_mov_b64_e32 v[26:27], 0
	v_mov_b64_e32 v[28:29], 0
	v_mov_b64_e32 v[30:31], 0
	v_mov_b64_e32 v[32:33], 0
	v_mov_b64_e32 v[34:35], 0
	v_mov_b64_e32 v[36:37], 0
	v_mov_b64_e32 v[38:39], 0
	v_mov_b64_e32 v[40:41], 0
	v_mov_b64_e32 v[42:43], 0
	v_mov_b64_e32 v[44:45], 0
	v_mov_b64_e32 v[46:47], 0
	v_mov_b64_e32 v[48:49], 0
	v_mov_b64_e32 v[50:51], 0
	v_mov_b64_e32 v[52:53], 0
	v_mov_b64_e32 v[54:55], 0
	v_mov_b64_e32 v[56:57], 0
	v_mov_b64_e32 v[58:59], 0
	v_mov_b64_e32 v[60:61], 0
	v_mov_b64_e32 v[62:63], 0
	v_mov_b64_e32 v[64:65], 0
	v_mov_b64_e32 v[66:67], 0
	v_mov_b64_e32 v[68:69], 0
	v_mov_b64_e32 v[70:71], 0
	v_mov_b64_e32 v[72:73], 0
	v_mov_b64_e32 v[74:75], 0
	v_mov_b64_e32 v[76:77], 0
	v_mov_b64_e32 v[78:79], 0
	v_mov_b64_e32 v[80:81], 0
	v_mov_b64_e32 v[82:83], 0
	v_mov_b64_e32 v[84:85], 0
	v_mov_b64_e32 v[86:87], 0
	v_mov_b64_e32 v[88:89], 0
	v_mov_b64_e32 v[90:91], 0
	v_mov_b64_e32 v[92:93], 0
	v_mov_b64_e32 v[94:95], 0
	v_mov_b64_e32 v[96:97], 0
	v_mov_b64_e32 v[98:99], 0
	v_mov_b64_e32 v[100:101], 0
	v_mov_b64_e32 v[102:103], 0
	v_mov_b64_e32 v[104:105], 0
	v_mov_b64_e32 v[106:107], 0
	v_mov_b64_e32 v[108:109], 0
	v_mov_b64_e32 v[110:111], 0
	v_mov_b64_e32 v[112:113], 0
	v_mov_b64_e32 v[114:115], 0
	v_mov_b64_e32 v[116:117], 0
	v_mov_b64_e32 v[118:119], 0
	v_mov_b64_e32 v[120:121], 0
	v_mov_b64_e32 v[122:123], 0
	v_mov_b64_e32 v[124:125], 0
	v_mov_b64_e32 v[126:127], 0
	s_addc_u32 vcc_hi, s93, 0
	s_mov_b32 s66, -2
	v_mov_b32_e32 v129, v159
	v_mov_b32_e32 v131, v167
	v_mov_b32_e32 v133, v173
	v_mov_b32_e32 v135, v175
	v_mov_b32_e32 v139, v163
	v_add_u32_e32 v141, 0x18000, v129
	v_add_u32_e32 v223, 0x1c000, v129
	s_cmp_lg_u32 s10, 0
	s_cbranch_scc0 .Lspf0_pre
	s_add_i32 m0, s3, 0xc000
	s_nop 0
	global_load_lds_dwordx4 v138, s[90:91]
	s_add_u32 s98, s90, 0x20000
	s_addc_u32 s99, s91, 0
	s_add_i32 m0, s3, 0xd000
	s_nop 0
	global_load_lds_dwordx4 v138, s[98:99]
	s_add_u32 s98, s90, 0xfff80000
	s_addc_u32 s99, s91, -1
	s_add_i32 m0, s3, 0x8000
	s_nop 0
	global_load_lds_dwordx4 v138, s[98:99]
	s_add_u32 s98, s90, 0xfffa0000
	s_addc_u32 s99, s91, -1
	s_add_i32 m0, s3, 0x9000
	s_nop 0
	global_load_lds_dwordx4 v138, s[98:99]
.Lspf0_pre:
.LBB0_127:
	s_add_u32 s67, s90, 0xfff80080
	s_addc_u32 s74, s91, -1
	s_cmp_eq_u32 s66, 28
	s_cselect_b32 s95, s12, s74
	s_cselect_b32 s94, s13, s67
	s_cselect_b32 s93, s71, vcc_hi
	s_cselect_b32 s92, s73, vcc_lo
	s_cmp_lg_u32 s10, 0
	s_cbranch_scc0 .Lspf0_a_h1
	s_add_u32 s98, vcc_lo, 0xffffff80
	s_addc_u32 s99, vcc_hi, -1
	s_add_i32 m0, s3, 0x18000
	ds_read_b128 v[146:149], v131
	ds_read_b128 v[150:153], v131 offset:1024
	ds_read_b128 v[168:171], v131 offset:2048
	global_load_lds_dwordx4 v132, s[98:99]
	s_add_i32 m0, s3, 0x1a000
	ds_read_b128 v[178:181], v131 offset:3072
	ds_read_b128 v[182:185], v133
	ds_read_b128 v[186:189], v133 offset:1024
	global_load_lds_dwordx4 v128, s[98:99]
	s_add_u32 s98, vcc_lo, 0x1ff80
	s_addc_u32 s99, vcc_hi, 0
	s_add_i32 m0, s3, 0x19000
	ds_read_b128 v[190:193], v133 offset:2048
	ds_read_b128 v[194:197], v133 offset:3072
	ds_read_b128 v[198:201], v135
	global_load_lds_dwordx4 v132, s[98:99]
	s_add_i32 m0, s3, 0x1b000
	ds_read_b128 v[202:205], v135 offset:1024
	ds_read_b128 v[206:209], v135 offset:2048
	ds_read_b128 v[210:213], v135 offset:3072
	global_load_lds_dwordx4 v128, s[98:99]
	s_add_u32 s98, vcc_lo, 0x7ff80
	s_addc_u32 s99, vcc_hi, 0
	s_add_i32 m0, s3, 0x1c000
	ds_read_b128 v[218:221], v135 offset:4096
	ds_read_b128 v[224:227], v135 offset:5120
	ds_read_b128 v[228:231], v135 offset:6144
	global_load_lds_dwordx4 v132, s[98:99]
	s_add_i32 m0, s3, 0x1e000
	ds_read_b128 v[232:235], v135 offset:7168
	ds_read_b128 v[236:239], v135 offset:16384
	ds_read_b128 v[240:243], v135 offset:17408
	global_load_lds_dwordx4 v128, s[98:99]
	s_add_u32 s98, vcc_lo, 0x9ff80
	s_addc_u32 s99, vcc_hi, 0
	s_add_i32 m0, s3, 0x1d000
	ds_read_b128 v[244:247], v135 offset:18432
	ds_read_b128 v[248:251], v135 offset:19456
	ds_read_b128 v[172:175], v135 offset:20480
	global_load_lds_dwordx4 v132, s[98:99]
	s_add_i32 m0, s3, 0x1f000
	ds_read_b128 v[156:159], v135 offset:21504
	ds_read_b128 v[160:163], v135 offset:22528
	ds_read_b128 v[164:167], v135 offset:23552
	global_load_lds_dwordx4 v128, s[98:99]
	s_branch .Lspf0_a_rd
; #define PG8_STAGE(bufoff, gbase, voff) do { _Pragma("unroll") for (int _i = 0; _i < 2; ++_i) \
;         __builtin_amdgcn_global_load_lds((const unsigned*)((const char*)(gbase) + (voff)[_i]), (PG8_LAS unsigned*)(lds + (bufoff) + ldsw + _i * 8192), 16, 0, 0); } while (0)
; #define PG8_LDA(dst, b, h) do { _Pragma("unroll") for (int m = 0; m < 4; ++m) _Pragma("unroll") for (int k = 0; k < 2; ++k) dst[m][k] = *(const PG8_LAS bf16x8*)(lds + PG8_SA(b, h) + aoff + m * 2048 + k * 1024); } while (0)
; #define PG8_LDB(dst, b, h) do { _Pragma("unroll") for (int n = 0; n < 2; ++n) _Pragma("unroll") for (int k = 0; k < 2; ++k) dst[n][k] = *(const PG8_LAS bf16x8*)(lds + PG8_SB(b, h) + boff + n * 2048 + k * 1024); } while (0)
; #define PG8_MMA(ai, bj, At, Bt) do { __builtin_amdgcn_s_setprio(1); _Pragma("unroll") for (int m = 0; m < 4; ++m) _Pragma("unroll") for (int n = 0; n < 2; ++n) _Pragma("unroll") for (int k = 0; k < 2; ++k) \
;         acc[ai][bj][m][n] = __builtin_amdgcn_mfma_f32_16x16x32_bf16(Bt[n][k], At[m][k], acc[ai][bj][m][n], 0, 0, 0); __builtin_amdgcn_s_setprio(0); } while (0)
; #define PG8_WAIT_V(n) asm volatile("s_waitcnt vmcnt(" #n ")" ::: "memory")
; #define PG8_WAIT_L(n) asm volatile("s_waitcnt lgkmcnt(" #n ")" ::: "memory")
; #define PG8_BAR __builtin_amdgcn_s_barrier()
; #define PG8_SCHED __builtin_amdgcn_sched_barrier(0)
; template <class Epi, class Sched, bool ALIGN_EPI = false, bool SP2 = false>
; __device__ __forceinline__ void gemm_phase(PG8_LAS unsigned char* lds, const Gemm g, const Sched& S, const Epi& E) {
;     ...
;             PG8_LDB(B0, 0, 0); PG8_LDB(B1, 0, 1); PG8_SCHED; PG8_LDA(At, 0, 0); PG8_STAGE(PG8_SA(1, 1), a1 + hstep, voffA);
;             PG8_WAIT_V(8); PG8_WAIT_L(0); PG8_BAR; PG8_MMA(0, 0, At, B0); PG8_MMA(0, 1, At, B1); PG8_BAR; PG8_SCHED;
;             PG8_LDA(At, 0, 1); PG8_STAGE(PG8_SB(0, 0), b2, voffB); PG8_STAGE(PG8_SB(0, 1), b2 + hstep, voffB); PG8_STAGE(PG8_SA(0, 0), a2, voffA);
;             PG8_WAIT_V(8); PG8_WAIT_L(0); PG8_BAR; PG8_MMA(1, 0, At, B0); PG8_MMA(1, 1, At, B1); PG8_BAR; PG8_SCHED;
.Lspf0_a_h1:
	s_add_u32 s98, s90, 0xfff80000
	s_addc_u32 s99, s91, -1
	s_add_i32 m0, s3, 0xa000
	ds_read_b128 v[146:149], v131
	ds_read_b128 v[150:153], v131 offset:1024
	ds_read_b128 v[168:171], v131 offset:2048
	global_load_lds_dwordx4 v140, s[98:99]
	s_add_u32 s98, s90, 0xfff60000
	s_addc_u32 s99, s91, -1
	s_add_i32 m0, s3, 0x9000
	ds_read_b128 v[178:181], v131 offset:3072
	ds_read_b128 v[182:185], v133
	ds_read_b128 v[186:189], v133 offset:1024
	global_load_lds_dwordx4 v140, s[98:99]
	s_add_i32 m0, s3, 0xe000
	ds_read_b128 v[190:193], v133 offset:2048
	ds_read_b128 v[194:197], v133 offset:3072
	ds_read_b128 v[198:201], v135
	global_load_lds_dwordx4 v140, s[90:91]
	s_add_u32 s98, s90, 0xfffe0000
	s_addc_u32 s99, s91, -1
	s_add_i32 m0, s3, 0xd000
	ds_read_b128 v[202:205], v135 offset:1024
	ds_read_b128 v[206:209], v135 offset:2048
	ds_read_b128 v[210:213], v135 offset:3072
	global_load_lds_dwordx4 v140, s[98:99]
	s_add_i32 m0, s3, 0x0
	ds_read_b128 v[218:221], v135 offset:4096
	ds_read_b128 v[224:227], v135 offset:5120
	ds_read_b128 v[228:231], v135 offset:6144
	global_load_lds_dwordx4 v134, s[94:95]
	s_add_u32 s98, s94, 0xfffe0000
	s_addc_u32 s99, s95, -1
	s_add_i32 m0, s3, 0xfffff000
	ds_read_b128 v[232:235], v135 offset:7168
	ds_read_b128 v[236:239], v135 offset:16384
	ds_read_b128 v[240:243], v135 offset:17408
	global_load_lds_dwordx4 v134, s[98:99]
	s_add_u32 s98, s94, 0x80000
	s_addc_u32 s99, s95, 0
	s_add_i32 m0, s3, 0x4000
	ds_read_b128 v[244:247], v135 offset:18432
	ds_read_b128 v[248:251], v135 offset:19456
	ds_read_b128 v[172:175], v135 offset:20480
	global_load_lds_dwordx4 v134, s[98:99]
	s_add_u32 s98, s94, 0x60000
	s_addc_u32 s99, s95, 0
	s_add_i32 m0, s3, 0x3000
	ds_read_b128 v[156:159], v135 offset:21504
	ds_read_b128 v[160:163], v135 offset:22528
	ds_read_b128 v[164:167], v135 offset:23552
	global_load_lds_dwordx4 v134, s[98:99]
.Lspf0_a_rd:
	s_waitcnt lgkmcnt(0)
	s_setprio 1
	s_barrier
	v_mfma_f32_16x16x32_bf16 v[124:127], v[146:149], v[198:201], v[124:127]
	v_mfma_f32_16x16x32_bf16 v[120:123], v[168:171], v[198:201], v[120:123]
	v_mfma_f32_16x16x32_bf16 v[108:111], v[146:149], v[206:209], v[108:111]
	v_mfma_f32_16x16x32_bf16 v[104:107], v[168:171], v[206:209], v[104:107]
	v_mfma_f32_16x16x32_bf16 v[92:95], v[146:149], v[218:221], v[92:95]
	v_mfma_f32_16x16x32_bf16 v[88:91], v[168:171], v[218:221], v[88:91]
	v_mfma_f32_16x16x32_bf16 v[76:79], v[146:149], v[228:231], v[76:79]
	v_mfma_f32_16x16x32_bf16 v[72:75], v[168:171], v[228:231], v[72:75]
	v_mfma_f32_16x16x32_bf16 v[124:127], v[150:153], v[202:205], v[124:127]
	v_mfma_f32_16x16x32_bf16 v[120:123], v[178:181], v[202:205], v[120:123]
	v_mfma_f32_16x16x32_bf16 v[108:111], v[150:153], v[210:213], v[108:111]
	v_mfma_f32_16x16x32_bf16 v[104:107], v[178:181], v[210:213], v[104:107]
	v_mfma_f32_16x16x32_bf16 v[92:95], v[150:153], v[224:227], v[92:95]
	v_mfma_f32_16x16x32_bf16 v[88:91], v[178:181], v[224:227], v[88:91]
	v_mfma_f32_16x16x32_bf16 v[76:79], v[150:153], v[232:235], v[76:79]
	v_mfma_f32_16x16x32_bf16 v[72:75], v[178:181], v[232:235], v[72:75]
	v_mfma_f32_16x16x32_bf16 v[116:119], v[182:185], v[198:201], v[116:119]
	v_mfma_f32_16x16x32_bf16 v[112:115], v[190:193], v[198:201], v[112:115]
	v_mfma_f32_16x16x32_bf16 v[100:103], v[182:185], v[206:209], v[100:103]
	v_mfma_f32_16x16x32_bf16 v[96:99], v[190:193], v[206:209], v[96:99]
	v_mfma_f32_16x16x32_bf16 v[84:87], v[182:185], v[218:221], v[84:87]
	v_mfma_f32_16x16x32_bf16 v[80:83], v[190:193], v[218:221], v[80:83]
	v_mfma_f32_16x16x32_bf16 v[68:71], v[182:185], v[228:231], v[68:71]
	v_mfma_f32_16x16x32_bf16 v[64:67], v[190:193], v[228:231], v[64:67]
	v_mfma_f32_16x16x32_bf16 v[116:119], v[186:189], v[202:205], v[116:119]
	v_mfma_f32_16x16x32_bf16 v[112:115], v[194:197], v[202:205], v[112:115]
	v_mfma_f32_16x16x32_bf16 v[100:103], v[186:189], v[210:213], v[100:103]
	v_mfma_f32_16x16x32_bf16 v[96:99], v[194:197], v[210:213], v[96:99]
	v_mfma_f32_16x16x32_bf16 v[84:87], v[186:189], v[224:227], v[84:87]
	v_mfma_f32_16x16x32_bf16 v[80:83], v[194:197], v[224:227], v[80:83]
	v_mfma_f32_16x16x32_bf16 v[68:71], v[186:189], v[232:235], v[68:71]
	v_mfma_f32_16x16x32_bf16 v[64:67], v[194:197], v[232:235], v[64:67]
	v_mfma_f32_16x16x32_bf16 v[60:63], v[146:149], v[236:239], v[60:63]
	v_mfma_f32_16x16x32_bf16 v[56:59], v[168:171], v[236:239], v[56:59]
	v_mfma_f32_16x16x32_bf16 v[44:47], v[146:149], v[244:247], v[44:47]
	v_mfma_f32_16x16x32_bf16 v[40:43], v[168:171], v[244:247], v[40:43]
	v_mfma_f32_16x16x32_bf16 v[28:31], v[146:149], v[172:175], v[28:31]
	v_mfma_f32_16x16x32_bf16 v[24:27], v[168:171], v[172:175], v[24:27]
	v_mfma_f32_16x16x32_bf16 v[12:15], v[146:149], v[160:163], v[12:15]
	v_mfma_f32_16x16x32_bf16 v[8:11], v[168:171], v[160:163], v[8:11]
	v_mfma_f32_16x16x32_bf16 v[60:63], v[150:153], v[240:243], v[60:63]
	v_mfma_f32_16x16x32_bf16 v[56:59], v[178:181], v[240:243], v[56:59]
	v_mfma_f32_16x16x32_bf16 v[44:47], v[150:153], v[248:251], v[44:47]
	v_mfma_f32_16x16x32_bf16 v[40:43], v[178:181], v[248:251], v[40:43]
	v_mfma_f32_16x16x32_bf16 v[28:31], v[150:153], v[156:159], v[28:31]
	v_mfma_f32_16x16x32_bf16 v[24:27], v[178:181], v[156:159], v[24:27]
	v_mfma_f32_16x16x32_bf16 v[12:15], v[150:153], v[164:167], v[12:15]
	v_mfma_f32_16x16x32_bf16 v[8:11], v[178:181], v[164:167], v[8:11]
	v_mfma_f32_16x16x32_bf16 v[52:55], v[182:185], v[236:239], v[52:55]
	v_mfma_f32_16x16x32_bf16 v[48:51], v[190:193], v[236:239], v[48:51]
	v_mfma_f32_16x16x32_bf16 v[36:39], v[182:185], v[244:247], v[36:39]
	v_mfma_f32_16x16x32_bf16 v[32:35], v[190:193], v[244:247], v[32:35]
	v_mfma_f32_16x16x32_bf16 v[20:23], v[182:185], v[172:175], v[20:23]
	v_mfma_f32_16x16x32_bf16 v[16:19], v[190:193], v[172:175], v[16:19]
	v_mfma_f32_16x16x32_bf16 v[4:7], v[182:185], v[160:163], v[4:7]
	v_mfma_f32_16x16x32_bf16 v[0:3], v[190:193], v[160:163], v[0:3]
	v_mfma_f32_16x16x32_bf16 v[52:55], v[186:189], v[240:243], v[52:55]
	v_mfma_f32_16x16x32_bf16 v[48:51], v[194:197], v[240:243], v[48:51]
	v_mfma_f32_16x16x32_bf16 v[36:39], v[186:189], v[248:251], v[36:39]
	v_mfma_f32_16x16x32_bf16 v[32:35], v[194:197], v[248:251], v[32:35]
	v_mfma_f32_16x16x32_bf16 v[20:23], v[186:189], v[156:159], v[20:23]
	v_mfma_f32_16x16x32_bf16 v[16:19], v[194:197], v[156:159], v[16:19]
	v_mfma_f32_16x16x32_bf16 v[4:7], v[186:189], v[164:167], v[4:7]
	v_mfma_f32_16x16x32_bf16 v[0:3], v[194:197], v[164:167], v[0:3]
	s_waitcnt vmcnt(0)
	s_barrier
; #define PG8_STAGE(bufoff, gbase, voff) do { _Pragma("unroll") for (int _i = 0; _i < 2; ++_i) \
;         __builtin_amdgcn_global_load_lds((const unsigned*)((const char*)(gbase) + (voff)[_i]), (PG8_LAS unsigned*)(lds + (bufoff) + ldsw + _i * 8192), 16, 0, 0); } while (0)
; #define PG8_LDA(dst, b, h) do { _Pragma("unroll") for (int m = 0; m < 4; ++m) _Pragma("unroll") for (int k = 0; k < 2; ++k) dst[m][k] = *(const PG8_LAS bf16x8*)(lds + PG8_SA(b, h) + aoff + m * 2048 + k * 1024); } while (0)
; #define PG8_LDB(dst, b, h) do { _Pragma("unroll") for (int n = 0; n < 2; ++n) _Pragma("unroll") for (int k = 0; k < 2; ++k) dst[n][k] = *(const PG8_LAS bf16x8*)(lds + PG8_SB(b, h) + boff + n * 2048 + k * 1024); } while (0)
; #define PG8_MMA(ai, bj, At, Bt) do { __builtin_amdgcn_s_setprio(1); _Pragma("unroll") for (int m = 0; m < 4; ++m) _Pragma("unroll") for (int n = 0; n < 2; ++n) _Pragma("unroll") for (int k = 0; k < 2; ++k) \
;         acc[ai][bj][m][n] = __builtin_amdgcn_mfma_f32_16x16x32_bf16(Bt[n][k], At[m][k], acc[ai][bj][m][n], 0, 0, 0); __builtin_amdgcn_s_setprio(0); } while (0)
; #define PG8_WAIT_V(n) asm volatile("s_waitcnt vmcnt(" #n ")" ::: "memory")
; #define PG8_WAIT_L(n) asm volatile("s_waitcnt lgkmcnt(" #n ")" ::: "memory")
; #define PG8_BAR __builtin_amdgcn_s_barrier()
; #define PG8_SCHED __builtin_amdgcn_sched_barrier(0)
; template <class Epi, class Sched, bool ALIGN_EPI = false, bool SP2 = false>
; __device__ __forceinline__ void gemm_phase(PG8_LAS unsigned char* lds, const Gemm g, const Sched& S, const Epi& E) {
;     ...
;             PG8_LDA(At, 0, 1); PG8_STAGE(PG8_SB(0, 0), b2, voffB); PG8_STAGE(PG8_SB(0, 1), b2 + hstep, voffB); PG8_STAGE(PG8_SA(0, 0), a2, voffA);
;             PG8_WAIT_V(8); PG8_WAIT_L(0); PG8_BAR; PG8_MMA(1, 0, At, B0); PG8_MMA(1, 1, At, B1); PG8_BAR; PG8_SCHED;
;             PG8_LDB(B0, 1, 0); PG8_LDB(B1, 1, 1); PG8_SCHED; PG8_LDA(At, 1, 0); PG8_STAGE(PG8_SA(0, 1), a2 + hstep, voffA);
;             PG8_WAIT_V(8); PG8_WAIT_L(0); PG8_BAR; PG8_MMA(0, 0, At, B0); PG8_MMA(0, 1, At, B1); PG8_BAR; PG8_SCHED;
;             PG8_LDA(At, 1, 1); PG8_STAGE(PG8_SB(1, 0), b3, voffB); PG8_STAGE(PG8_SB(1, 1), b3 + hstep, voffB); PG8_STAGE(PG8_SA(1, 0), a3, voffA);
	s_setprio 0
	s_cmp_lg_u32 s10, 0
	s_cbranch_scc0 .Lspf0_b_h1
	s_add_i32 m0, s3, 0x10000
	ds_read_b128 v[146:149], v141
	ds_read_b128 v[150:153], v141 offset:1024
	ds_read_b128 v[168:171], v141 offset:2048
	global_load_lds_dwordx4 v132, s[92:93]
	s_add_i32 m0, s3, 0x12000
	ds_read_b128 v[178:181], v141 offset:3072
	ds_read_b128 v[182:185], v223
	ds_read_b128 v[186:189], v223 offset:1024
	global_load_lds_dwordx4 v128, s[92:93]
	s_add_u32 s98, s92, 0x20000
	s_addc_u32 s99, s93, 0
	s_add_i32 m0, s3, 0x11000
	ds_read_b128 v[190:193], v223 offset:2048
	ds_read_b128 v[194:197], v223 offset:3072
	ds_read_b128 v[198:201], v135 offset:32768
	global_load_lds_dwordx4 v132, s[98:99]
	s_add_i32 m0, s3, 0x13000
	ds_read_b128 v[202:205], v135 offset:33792
	ds_read_b128 v[206:209], v135 offset:34816
	ds_read_b128 v[210:213], v135 offset:35840
	global_load_lds_dwordx4 v128, s[98:99]
	s_add_u32 s98, s92, 0x80000
	s_addc_u32 s99, s93, 0
	s_add_i32 m0, s3, 0x14000
	ds_read_b128 v[218:221], v135 offset:36864
	ds_read_b128 v[224:227], v135 offset:37888
	ds_read_b128 v[228:231], v135 offset:38912
	global_load_lds_dwordx4 v132, s[98:99]
	s_add_i32 m0, s3, 0x16000
	ds_read_b128 v[232:235], v135 offset:39936
	ds_read_b128 v[236:239], v135 offset:49152
	ds_read_b128 v[240:243], v135 offset:50176
	global_load_lds_dwordx4 v128, s[98:99]
	s_add_u32 s98, s92, 0xa0000
	s_addc_u32 s99, s93, 0
	s_add_i32 m0, s3, 0x15000
	ds_read_b128 v[244:247], v135 offset:51200
	ds_read_b128 v[248:251], v135 offset:52224
	ds_read_b128 v[172:175], v135 offset:53248
	global_load_lds_dwordx4 v132, s[98:99]
	s_add_i32 m0, s3, 0x17000
	ds_read_b128 v[156:159], v135 offset:54272
	ds_read_b128 v[160:163], v135 offset:55296
	ds_read_b128 v[164:167], v135 offset:56320
	global_load_lds_dwordx4 v128, s[98:99]
	s_branch .Lspf0_b_rd
.Lspf0_b_h1:
	s_add_i32 m0, s3, 0x2000
	ds_read_b128 v[146:149], v141
	ds_read_b128 v[150:153], v141 offset:1024
	ds_read_b128 v[168:171], v141 offset:2048
	global_load_lds_dwordx4 v130, s[94:95]
	s_add_u32 s98, s94, 0xfffe0000
	s_addc_u32 s99, s95, -1
	s_add_i32 m0, s3, 0x1000
	ds_read_b128 v[178:181], v141 offset:3072
	ds_read_b128 v[182:185], v223
	ds_read_b128 v[186:189], v223 offset:1024
	global_load_lds_dwordx4 v130, s[98:99]
	s_add_u32 s98, s94, 0x80000
	s_addc_u32 s99, s95, 0
	s_add_i32 m0, s3, 0x6000
	ds_read_b128 v[190:193], v223 offset:2048
	ds_read_b128 v[194:197], v223 offset:3072
	ds_read_b128 v[198:201], v135 offset:32768
	global_load_lds_dwordx4 v130, s[98:99]
	s_add_u32 s98, s94, 0x60000
	s_addc_u32 s99, s95, 0
	s_add_i32 m0, s3, 0x5000
	ds_read_b128 v[202:205], v135 offset:33792
	ds_read_b128 v[206:209], v135 offset:34816
	ds_read_b128 v[210:213], v135 offset:35840
	global_load_lds_dwordx4 v130, s[98:99]
	s_add_u32 s98, s94, 0x80
	s_addc_u32 s99, s95, 0
	s_add_i32 m0, s3, 0x8000
	ds_read_b128 v[218:221], v135 offset:36864
	ds_read_b128 v[224:227], v135 offset:37888
	ds_read_b128 v[228:231], v135 offset:38912
	global_load_lds_dwordx4 v134, s[98:99]
	s_add_u32 s98, s94, 0xfffe0080
	s_addc_u32 s99, s95, -1
	s_add_i32 m0, s3, 0x7000
	ds_read_b128 v[232:235], v135 offset:39936
	ds_read_b128 v[236:239], v135 offset:49152
	ds_read_b128 v[240:243], v135 offset:50176
	global_load_lds_dwordx4 v134, s[98:99]
	s_add_u32 s98, s94, 0x80080
	s_addc_u32 s99, s95, 0
	s_add_i32 m0, s3, 0xc000
	ds_read_b128 v[244:247], v135 offset:51200
	ds_read_b128 v[248:251], v135 offset:52224
	ds_read_b128 v[172:175], v135 offset:53248
	global_load_lds_dwordx4 v134, s[98:99]
	s_add_u32 s98, s94, 0x60080
	s_addc_u32 s99, s95, 0
	s_add_i32 m0, s3, 0xb000
	ds_read_b128 v[156:159], v135 offset:54272
	ds_read_b128 v[160:163], v135 offset:55296
	ds_read_b128 v[164:167], v135 offset:56320
	global_load_lds_dwordx4 v134, s[98:99]
; #define PG8_STAGE(bufoff, gbase, voff) do { _Pragma("unroll") for (int _i = 0; _i < 2; ++_i) \
;         __builtin_amdgcn_global_load_lds((const unsigned*)((const char*)(gbase) + (voff)[_i]), (PG8_LAS unsigned*)(lds + (bufoff) + ldsw + _i * 8192), 16, 0, 0); } while (0)
; #define PG8_LDA(dst, b, h) do { _Pragma("unroll") for (int m = 0; m < 4; ++m) _Pragma("unroll") for (int k = 0; k < 2; ++k) dst[m][k] = *(const PG8_LAS bf16x8*)(lds + PG8_SA(b, h) + aoff + m * 2048 + k * 1024); } while (0)
; #define PG8_MMA(ai, bj, At, Bt) do { __builtin_amdgcn_s_setprio(1); _Pragma("unroll") for (int m = 0; m < 4; ++m) _Pragma("unroll") for (int n = 0; n < 2; ++n) _Pragma("unroll") for (int k = 0; k < 2; ++k) \
;         acc[ai][bj][m][n] = __builtin_amdgcn_mfma_f32_16x16x32_bf16(Bt[n][k], At[m][k], acc[ai][bj][m][n], 0, 0, 0); __builtin_amdgcn_s_setprio(0); } while (0)
; #define PG8_WAIT_V(n) asm volatile("s_waitcnt vmcnt(" #n ")" ::: "memory")
; #define PG8_WAIT_L(n) asm volatile("s_waitcnt lgkmcnt(" #n ")" ::: "memory")
; #define PG8_BAR __builtin_amdgcn_s_barrier()
; #define PG8_SCHED __builtin_amdgcn_sched_barrier(0)
; template <class Epi, class Sched, bool ALIGN_EPI = false, bool SP2 = false>
; __device__ __forceinline__ void gemm_phase(PG8_LAS unsigned char* lds, const Gemm g, const Sched& S, const Epi& E) {
;     ...
;             PG8_WAIT_V(8); PG8_WAIT_L(0); PG8_BAR; PG8_MMA(0, 0, At, B0); PG8_MMA(0, 1, At, B1); PG8_BAR; PG8_SCHED;
;             PG8_LDA(At, 1, 1); PG8_STAGE(PG8_SB(1, 0), b3, voffB); PG8_STAGE(PG8_SB(1, 1), b3 + hstep, voffB); PG8_STAGE(PG8_SA(1, 0), a3, voffA);
;             PG8_WAIT_V(8); PG8_WAIT_L(0); PG8_BAR; PG8_MMA(1, 0, At, B0); PG8_MMA(1, 1, At, B1); PG8_BAR; PG8_SCHED;
.Lspf0_b_rd:
	s_waitcnt lgkmcnt(0)
	s_setprio 1
	s_barrier
	v_mfma_f32_16x16x32_bf16 v[124:127], v[146:149], v[198:201], v[124:127]
	v_mfma_f32_16x16x32_bf16 v[120:123], v[168:171], v[198:201], v[120:123]
	v_mfma_f32_16x16x32_bf16 v[108:111], v[146:149], v[206:209], v[108:111]
	v_mfma_f32_16x16x32_bf16 v[104:107], v[168:171], v[206:209], v[104:107]
	v_mfma_f32_16x16x32_bf16 v[92:95], v[146:149], v[218:221], v[92:95]
	v_mfma_f32_16x16x32_bf16 v[88:91], v[168:171], v[218:221], v[88:91]
	v_mfma_f32_16x16x32_bf16 v[76:79], v[146:149], v[228:231], v[76:79]
	v_mfma_f32_16x16x32_bf16 v[72:75], v[168:171], v[228:231], v[72:75]
	v_mfma_f32_16x16x32_bf16 v[124:127], v[150:153], v[202:205], v[124:127]
	v_mfma_f32_16x16x32_bf16 v[120:123], v[178:181], v[202:205], v[120:123]
	v_mfma_f32_16x16x32_bf16 v[108:111], v[150:153], v[210:213], v[108:111]
	v_mfma_f32_16x16x32_bf16 v[104:107], v[178:181], v[210:213], v[104:107]
	v_mfma_f32_16x16x32_bf16 v[92:95], v[150:153], v[224:227], v[92:95]
	v_mfma_f32_16x16x32_bf16 v[88:91], v[178:181], v[224:227], v[88:91]
	v_mfma_f32_16x16x32_bf16 v[76:79], v[150:153], v[232:235], v[76:79]
	v_mfma_f32_16x16x32_bf16 v[72:75], v[178:181], v[232:235], v[72:75]
	v_mfma_f32_16x16x32_bf16 v[116:119], v[182:185], v[198:201], v[116:119]
	v_mfma_f32_16x16x32_bf16 v[112:115], v[190:193], v[198:201], v[112:115]
	v_mfma_f32_16x16x32_bf16 v[100:103], v[182:185], v[206:209], v[100:103]
	v_mfma_f32_16x16x32_bf16 v[96:99], v[190:193], v[206:209], v[96:99]
	v_mfma_f32_16x16x32_bf16 v[84:87], v[182:185], v[218:221], v[84:87]
	v_mfma_f32_16x16x32_bf16 v[80:83], v[190:193], v[218:221], v[80:83]
	v_mfma_f32_16x16x32_bf16 v[68:71], v[182:185], v[228:231], v[68:71]
	v_mfma_f32_16x16x32_bf16 v[64:67], v[190:193], v[228:231], v[64:67]
	v_mfma_f32_16x16x32_bf16 v[116:119], v[186:189], v[202:205], v[116:119]
	v_mfma_f32_16x16x32_bf16 v[112:115], v[194:197], v[202:205], v[112:115]
	v_mfma_f32_16x16x32_bf16 v[100:103], v[186:189], v[210:213], v[100:103]
	v_mfma_f32_16x16x32_bf16 v[96:99], v[194:197], v[210:213], v[96:99]
	v_mfma_f32_16x16x32_bf16 v[84:87], v[186:189], v[224:227], v[84:87]
	v_mfma_f32_16x16x32_bf16 v[80:83], v[194:197], v[224:227], v[80:83]
	v_mfma_f32_16x16x32_bf16 v[68:71], v[186:189], v[232:235], v[68:71]
	v_mfma_f32_16x16x32_bf16 v[64:67], v[194:197], v[232:235], v[64:67]
	v_mfma_f32_16x16x32_bf16 v[60:63], v[146:149], v[236:239], v[60:63]
	v_mfma_f32_16x16x32_bf16 v[56:59], v[168:171], v[236:239], v[56:59]
	v_mfma_f32_16x16x32_bf16 v[44:47], v[146:149], v[244:247], v[44:47]
	v_mfma_f32_16x16x32_bf16 v[40:43], v[168:171], v[244:247], v[40:43]
	v_mfma_f32_16x16x32_bf16 v[28:31], v[146:149], v[172:175], v[28:31]
	v_mfma_f32_16x16x32_bf16 v[24:27], v[168:171], v[172:175], v[24:27]
	v_mfma_f32_16x16x32_bf16 v[12:15], v[146:149], v[160:163], v[12:15]
	v_mfma_f32_16x16x32_bf16 v[8:11], v[168:171], v[160:163], v[8:11]
	v_mfma_f32_16x16x32_bf16 v[60:63], v[150:153], v[240:243], v[60:63]
	v_mfma_f32_16x16x32_bf16 v[56:59], v[178:181], v[240:243], v[56:59]
	v_mfma_f32_16x16x32_bf16 v[44:47], v[150:153], v[248:251], v[44:47]
	v_mfma_f32_16x16x32_bf16 v[40:43], v[178:181], v[248:251], v[40:43]
	v_mfma_f32_16x16x32_bf16 v[28:31], v[150:153], v[156:159], v[28:31]
	v_mfma_f32_16x16x32_bf16 v[24:27], v[178:181], v[156:159], v[24:27]
	v_mfma_f32_16x16x32_bf16 v[12:15], v[150:153], v[164:167], v[12:15]
	v_mfma_f32_16x16x32_bf16 v[8:11], v[178:181], v[164:167], v[8:11]
	v_mfma_f32_16x16x32_bf16 v[52:55], v[182:185], v[236:239], v[52:55]
	v_mfma_f32_16x16x32_bf16 v[48:51], v[190:193], v[236:239], v[48:51]
	v_mfma_f32_16x16x32_bf16 v[36:39], v[182:185], v[244:247], v[36:39]
	v_mfma_f32_16x16x32_bf16 v[32:35], v[190:193], v[244:247], v[32:35]
	v_mfma_f32_16x16x32_bf16 v[20:23], v[182:185], v[172:175], v[20:23]
	v_mfma_f32_16x16x32_bf16 v[16:19], v[190:193], v[172:175], v[16:19]
	v_mfma_f32_16x16x32_bf16 v[4:7], v[182:185], v[160:163], v[4:7]
	v_mfma_f32_16x16x32_bf16 v[0:3], v[190:193], v[160:163], v[0:3]
	v_mfma_f32_16x16x32_bf16 v[52:55], v[186:189], v[240:243], v[52:55]
	v_mfma_f32_16x16x32_bf16 v[48:51], v[194:197], v[240:243], v[48:51]
	v_mfma_f32_16x16x32_bf16 v[36:39], v[186:189], v[248:251], v[36:39]
	v_mfma_f32_16x16x32_bf16 v[32:35], v[194:197], v[248:251], v[32:35]
	v_mfma_f32_16x16x32_bf16 v[20:23], v[186:189], v[156:159], v[20:23]
	v_mfma_f32_16x16x32_bf16 v[16:19], v[194:197], v[156:159], v[16:19]
	v_mfma_f32_16x16x32_bf16 v[4:7], v[186:189], v[164:167], v[4:7]
	v_mfma_f32_16x16x32_bf16 v[0:3], v[194:197], v[164:167], v[0:3]
	s_waitcnt vmcnt(0)
	s_barrier
	s_setprio 0
	s_add_i32 s66, s66, 2
	s_add_u32 s90, s90, 0x100
	s_addc_u32 s91, s91, 0
	s_add_u32 vcc_lo, vcc_lo, 0x100
	s_addc_u32 vcc_hi, vcc_hi, 0
	s_cmp_gt_u32 s66, 29
	s_cbranch_scc0 .LBB0_127
	v_mov_b32_e32 v159, v129
	v_mov_b32_e32 v167, v131
	v_mov_b32_e32 v173, v133
	v_mov_b32_e32 v175, v135
	v_mov_b32_e32 v163, v139
	s_and_b64 vcc, exec, s[10:11]
	s_cbranch_vccz .LBB0_130
	s_barrier
